# attnB epilogue: 16 dwordx2 row stores per lane merged into 8 dwordx4 via v_permlane32_swap pairs
# speedup vs baseline: 1.0064x; 1.0064x over previous
; __device__ __forceinline__ void attnB_unit(const bf16* Q, const bf16* __restrict__ K, const bf16* __restrict__ V, bf16* O, long rowbase, int seq, int h, int q0, float lam, char* lds, LAS unsigned char* lds3) {
;     ...
;     __syncthreads();
;     if (c == 0) {
;         float ss = 0.f;
; #pragma unroll
;         for (int d0 = 0; d0 < 4; ++d0)
; #pragma unroll
;             for (int r = 0; r < 16; ++r) { const float v = o[d0][r] * rl - lam * X[(d0 * 16 + r) * 64]; o[d0][r] = v; ss += v * v; }
.LBB0_304:
	s_cmpk_gt_u32 s28, 0xff
	s_waitcnt lgkmcnt(0)
	s_barrier
	s_cbranch_scc1 .LBB0_265
	ds_read2st64_b32 v[4:5], v1 offset1:1
	ds_read2st64_b32 v[10:11], v1 offset0:2 offset1:3
	ds_read2st64_b32 v[14:15], v1 offset0:4 offset1:5
	ds_read2st64_b32 v[86:87], v1 offset0:14 offset1:15
	v_mov_b32_e32 v2, v66
	s_waitcnt lgkmcnt(3)
	v_mov_b32_e32 v3, v4
	v_mul_f32_e32 v4, v163, v4
	v_pk_fma_f32 v[2:3], v[162:163], v[2:3], v[4:5] op_sel_hi:[1,1,0] neg_lo:[0,0,1] neg_hi:[0,0,1]
	v_mov_b32_e32 v4, v67
	v_mul_f32_e32 v6, v163, v5
	v_pk_fma_f32 v[4:5], v[162:163], v[4:5], v[6:7] op_sel_hi:[1,1,0] neg_lo:[0,0,1] neg_hi:[0,0,1]
	ds_read2st64_b32 v[88:89], v1 offset0:16 offset1:17
	ds_read2st64_b32 v[96:97], v1 offset0:24 offset1:25
	ds_read2st64_b32 v[104:105], v1 offset0:32 offset1:33
	v_pk_mul_f32 v[6:7], v[4:5], v[4:5]
	ds_read2st64_b32 v[112:113], v1 offset0:40 offset1:41
	ds_read2st64_b32 v[114:115], v1 offset0:42 offset1:43
	ds_read2st64_b32 v[116:117], v1 offset0:44 offset1:45
	ds_read2st64_b32 v[118:119], v1 offset0:46 offset1:47
	v_pk_fma_f32 v[8:9], v[2:3], v[2:3], v[6:7]
	v_mov_b32_e32 v6, v68
	s_waitcnt lgkmcnt(9)
	v_mov_b32_e32 v7, v10
	v_mul_f32_e32 v10, v163, v10
	v_pk_fma_f32 v[6:7], v[162:163], v[6:7], v[10:11] op_sel_hi:[1,1,0] neg_lo:[0,0,1] neg_hi:[0,0,1]
	v_mov_b32_e32 v10, v69
	ds_read2st64_b32 v[68:69], v1 offset0:6 offset1:7
	v_pk_fma_f32 v[12:13], v[6:7], v[6:7], v[8:9]
	v_mul_f32_e32 v8, v163, v11
	v_pk_fma_f32 v[8:9], v[162:163], v[10:11], v[8:9] op_sel_hi:[1,1,0] neg_lo:[0,0,1] neg_hi:[0,0,1]
	v_mov_b32_e32 v10, v70
	s_waitcnt lgkmcnt(9)
	v_mov_b32_e32 v11, v14
	v_mul_f32_e32 v14, v163, v14
	v_pk_fma_f32 v[12:13], v[8:9], v[8:9], v[12:13]
	v_pk_fma_f32 v[10:11], v[162:163], v[10:11], v[14:15] op_sel_hi:[1,1,0] neg_lo:[0,0,1] neg_hi:[0,0,1]
	v_mov_b32_e32 v14, v71
	v_pk_fma_f32 v[66:67], v[10:11], v[10:11], v[12:13]
	v_mul_f32_e32 v12, v163, v15
	v_pk_fma_f32 v[12:13], v[162:163], v[14:15], v[12:13] op_sel_hi:[1,1,0] neg_lo:[0,0,1] neg_hi:[0,0,1]
	v_mov_b32_e32 v14, v72
	s_waitcnt lgkmcnt(0)
	v_mov_b32_e32 v15, v68
	v_mul_f32_e32 v68, v163, v68
	v_pk_fma_f32 v[14:15], v[162:163], v[14:15], v[68:69] op_sel_hi:[1,1,0] neg_lo:[0,0,1] neg_hi:[0,0,1]
	v_mov_b32_e32 v68, v73
	ds_read2st64_b32 v[72:73], v1 offset0:8 offset1:9
	ds_read2st64_b32 v[90:91], v1 offset0:18 offset1:19
	ds_read2st64_b32 v[98:99], v1 offset0:26 offset1:27
	ds_read2st64_b32 v[106:107], v1 offset0:34 offset1:35
	v_pk_fma_f32 v[66:67], v[12:13], v[12:13], v[66:67]
	ds_read2st64_b32 v[92:93], v1 offset0:20 offset1:21
	ds_read2st64_b32 v[100:101], v1 offset0:28 offset1:29
	ds_read2st64_b32 v[108:109], v1 offset0:36 offset1:37
	v_pk_fma_f32 v[70:71], v[14:15], v[14:15], v[66:67]
	v_mul_f32_e32 v66, v163, v69
	v_pk_fma_f32 v[66:67], v[162:163], v[68:69], v[66:67] op_sel_hi:[1,1,0] neg_lo:[0,0,1] neg_hi:[0,0,1]
	v_mov_b32_e32 v68, v74
	s_waitcnt lgkmcnt(6)
	v_mov_b32_e32 v69, v72
	v_mul_f32_e32 v72, v163, v72
	v_pk_fma_f32 v[70:71], v[66:67], v[66:67], v[70:71]
	v_pk_fma_f32 v[68:69], v[162:163], v[68:69], v[72:73] op_sel_hi:[1,1,0] neg_lo:[0,0,1] neg_hi:[0,0,1]
	v_mov_b32_e32 v72, v75
	v_pk_fma_f32 v[82:83], v[68:69], v[68:69], v[70:71]
	v_mul_f32_e32 v70, v163, v73
	v_pk_fma_f32 v[70:71], v[162:163], v[72:73], v[70:71] op_sel_hi:[1,1,0] neg_lo:[0,0,1] neg_hi:[0,0,1]
	v_mov_b32_e32 v72, v76
	v_pk_fma_f32 v[74:75], v[70:71], v[70:71], v[82:83]
	ds_read2st64_b32 v[82:83], v1 offset0:10 offset1:11
	ds_read2st64_b32 v[94:95], v1 offset0:22 offset1:23
	ds_read2st64_b32 v[102:103], v1 offset0:30 offset1:31
	ds_read2st64_b32 v[110:111], v1 offset0:38 offset1:39
	ds_read2st64_b32 v[120:121], v1 offset0:48 offset1:49
	ds_read2st64_b32 v[122:123], v1 offset0:50 offset1:51
	ds_read2st64_b32 v[124:125], v1 offset0:52 offset1:53
	ds_read2st64_b32 v[126:127], v1 offset0:54 offset1:55
	s_waitcnt lgkmcnt(7)
	v_mov_b32_e32 v73, v82
	v_mul_f32_e32 v76, v163, v82
	v_pk_fma_f32 v[72:73], v[162:163], v[72:73], v[76:77] op_sel_hi:[1,1,0] neg_lo:[0,0,1] neg_hi:[0,0,1]
	v_mov_b32_e32 v82, v77
	v_pk_fma_f32 v[84:85], v[72:73], v[72:73], v[74:75]
	v_mul_f32_e32 v74, v163, v83
	v_pk_fma_f32 v[74:75], v[162:163], v[82:83], v[74:75] op_sel_hi:[1,1,0] neg_lo:[0,0,1] neg_hi:[0,0,1]
	v_mov_b32_e32 v76, v78
	v_pk_fma_f32 v[82:83], v[74:75], v[74:75], v[84:85]
	ds_read2st64_b32 v[84:85], v1 offset0:12 offset1:13
	ds_read2st64_b32 v[128:129], v1 offset0:56 offset1:57
	ds_read2st64_b32 v[130:131], v1 offset0:58 offset1:59
	ds_read2st64_b32 v[132:133], v1 offset0:60 offset1:61
	s_waitcnt lgkmcnt(3)
; __device__ __forceinline__ void attnB_unit(const bf16* Q, const bf16* __restrict__ K, const bf16* __restrict__ V, bf16* O, long rowbase, int seq, int h, int q0, float lam, char* lds, LAS unsigned char* lds3) {
;     ...
;         for (int d0 = 0; d0 < 4; ++d0)
; #pragma unroll
;             for (int r = 0; r < 16; ++r) { const float v = o[d0][r] * rl - lam * X[(d0 * 16 + r) * 64]; o[d0][r] = v; ss += v * v; }
	v_mov_b32_e32 v77, v84
	v_mul_f32_e32 v78, v163, v84
	v_pk_fma_f32 v[76:77], v[162:163], v[76:77], v[78:79] op_sel_hi:[1,1,0] neg_lo:[0,0,1] neg_hi:[0,0,1]
	v_mov_b32_e32 v84, v79
	v_mul_f32_e32 v78, v163, v85
	v_pk_fma_f32 v[82:83], v[76:77], v[76:77], v[82:83]
	v_pk_fma_f32 v[78:79], v[162:163], v[84:85], v[78:79] op_sel_hi:[1,1,0] neg_lo:[0,0,1] neg_hi:[0,0,1]
	s_nop 0
	v_pk_fma_f32 v[84:85], v[78:79], v[78:79], v[82:83]
	v_mov_b32_e32 v82, v80
	v_mov_b32_e32 v83, v86
	v_mul_f32_e32 v80, v163, v86
	v_pk_fma_f32 v[82:83], v[162:163], v[82:83], v[80:81] op_sel_hi:[1,1,0] neg_lo:[0,0,1] neg_hi:[0,0,1]
	v_mov_b32_e32 v86, v81
	v_mul_f32_e32 v80, v163, v87
	v_pk_fma_f32 v[84:85], v[82:83], v[82:83], v[84:85]
	v_pk_fma_f32 v[80:81], v[162:163], v[86:87], v[80:81] op_sel_hi:[1,1,0] neg_lo:[0,0,1] neg_hi:[0,0,1]
	s_nop 0
	v_pk_fma_f32 v[86:87], v[80:81], v[80:81], v[84:85]
	v_mov_b32_e32 v84, v50
	v_mov_b32_e32 v85, v88
	v_mul_f32_e32 v50, v163, v88
	v_pk_fma_f32 v[84:85], v[162:163], v[84:85], v[50:51] op_sel_hi:[1,1,0] neg_lo:[0,0,1] neg_hi:[0,0,1]
	v_mov_b32_e32 v88, v51
	v_mul_f32_e32 v50, v163, v89
	v_pk_fma_f32 v[86:87], v[84:85], v[84:85], v[86:87]
	v_pk_fma_f32 v[50:51], v[162:163], v[88:89], v[50:51] op_sel_hi:[1,1,0] neg_lo:[0,0,1] neg_hi:[0,0,1]
	s_nop 0
	v_pk_fma_f32 v[88:89], v[50:51], v[50:51], v[86:87]
	v_mov_b32_e32 v86, v52
	v_mov_b32_e32 v87, v90
	v_mul_f32_e32 v52, v163, v90
	v_pk_fma_f32 v[86:87], v[162:163], v[86:87], v[52:53] op_sel_hi:[1,1,0] neg_lo:[0,0,1] neg_hi:[0,0,1]
	v_mov_b32_e32 v90, v53
	v_mul_f32_e32 v52, v163, v91
	v_pk_fma_f32 v[88:89], v[86:87], v[86:87], v[88:89]
	v_pk_fma_f32 v[52:53], v[162:163], v[90:91], v[52:53] op_sel_hi:[1,1,0] neg_lo:[0,0,1] neg_hi:[0,0,1]
	s_nop 0
	v_pk_fma_f32 v[90:91], v[52:53], v[52:53], v[88:89]
	v_mov_b32_e32 v88, v54
	v_mov_b32_e32 v89, v92
	v_mul_f32_e32 v54, v163, v92
	v_pk_fma_f32 v[88:89], v[162:163], v[88:89], v[54:55] op_sel_hi:[1,1,0] neg_lo:[0,0,1] neg_hi:[0,0,1]
	v_mov_b32_e32 v92, v55
	v_mul_f32_e32 v54, v163, v93
	v_pk_fma_f32 v[90:91], v[88:89], v[88:89], v[90:91]
	v_pk_fma_f32 v[54:55], v[162:163], v[92:93], v[54:55] op_sel_hi:[1,1,0] neg_lo:[0,0,1] neg_hi:[0,0,1]
	s_nop 0
	v_pk_fma_f32 v[92:93], v[54:55], v[54:55], v[90:91]
	v_mov_b32_e32 v90, v56
	v_mov_b32_e32 v91, v94
	v_mul_f32_e32 v56, v163, v94
	v_pk_fma_f32 v[90:91], v[162:163], v[90:91], v[56:57] op_sel_hi:[1,1,0] neg_lo:[0,0,1] neg_hi:[0,0,1]
	v_mov_b32_e32 v94, v57
	v_mul_f32_e32 v56, v163, v95
	v_pk_fma_f32 v[92:93], v[90:91], v[90:91], v[92:93]
	v_pk_fma_f32 v[56:57], v[162:163], v[94:95], v[56:57] op_sel_hi:[1,1,0] neg_lo:[0,0,1] neg_hi:[0,0,1]
	s_nop 0
	v_pk_fma_f32 v[94:95], v[56:57], v[56:57], v[92:93]
	v_mov_b32_e32 v92, v58
	v_mov_b32_e32 v93, v96
	v_mul_f32_e32 v58, v163, v96
	v_pk_fma_f32 v[92:93], v[162:163], v[92:93], v[58:59] op_sel_hi:[1,1,0] neg_lo:[0,0,1] neg_hi:[0,0,1]
	v_mov_b32_e32 v96, v59
	v_mul_f32_e32 v58, v163, v97
	v_pk_fma_f32 v[94:95], v[92:93], v[92:93], v[94:95]
	v_pk_fma_f32 v[58:59], v[162:163], v[96:97], v[58:59] op_sel_hi:[1,1,0] neg_lo:[0,0,1] neg_hi:[0,0,1]
	s_nop 0
	v_pk_fma_f32 v[96:97], v[58:59], v[58:59], v[94:95]
	v_mov_b32_e32 v94, v60
	v_mov_b32_e32 v95, v98
	v_mul_f32_e32 v60, v163, v98
	v_pk_fma_f32 v[94:95], v[162:163], v[94:95], v[60:61] op_sel_hi:[1,1,0] neg_lo:[0,0,1] neg_hi:[0,0,1]
	v_mov_b32_e32 v98, v61
	v_mul_f32_e32 v60, v163, v99
	v_pk_fma_f32 v[96:97], v[94:95], v[94:95], v[96:97]
	v_pk_fma_f32 v[60:61], v[162:163], v[98:99], v[60:61] op_sel_hi:[1,1,0] neg_lo:[0,0,1] neg_hi:[0,0,1]
	s_nop 0
	v_pk_fma_f32 v[98:99], v[60:61], v[60:61], v[96:97]
	v_mov_b32_e32 v96, v62
	v_mov_b32_e32 v97, v100
	v_mul_f32_e32 v62, v163, v100
	v_pk_fma_f32 v[96:97], v[162:163], v[96:97], v[62:63] op_sel_hi:[1,1,0] neg_lo:[0,0,1] neg_hi:[0,0,1]
	v_mov_b32_e32 v100, v63
	v_mul_f32_e32 v62, v163, v101
	v_pk_fma_f32 v[98:99], v[96:97], v[96:97], v[98:99]
	v_pk_fma_f32 v[62:63], v[162:163], v[100:101], v[62:63] op_sel_hi:[1,1,0] neg_lo:[0,0,1] neg_hi:[0,0,1]
	s_nop 0
	v_pk_fma_f32 v[100:101], v[62:63], v[62:63], v[98:99]
	v_mov_b32_e32 v98, v64
	v_mov_b32_e32 v99, v102
	v_mul_f32_e32 v64, v163, v102
	v_pk_fma_f32 v[98:99], v[162:163], v[98:99], v[64:65] op_sel_hi:[1,1,0] neg_lo:[0,0,1] neg_hi:[0,0,1]
	v_mov_b32_e32 v102, v65
	v_mul_f32_e32 v64, v163, v103
	v_pk_fma_f32 v[100:101], v[98:99], v[98:99], v[100:101]
	v_pk_fma_f32 v[64:65], v[162:163], v[102:103], v[64:65] op_sel_hi:[1,1,0] neg_lo:[0,0,1] neg_hi:[0,0,1]
	s_nop 0
	v_pk_fma_f32 v[102:103], v[64:65], v[64:65], v[100:101]
	v_mov_b32_e32 v100, v34
	v_mov_b32_e32 v101, v104
	v_mul_f32_e32 v34, v163, v104
	v_pk_fma_f32 v[100:101], v[162:163], v[100:101], v[34:35] op_sel_hi:[1,1,0] neg_lo:[0,0,1] neg_hi:[0,0,1]
	v_mov_b32_e32 v104, v35
	v_mul_f32_e32 v34, v163, v105
	v_pk_fma_f32 v[102:103], v[100:101], v[100:101], v[102:103]
	v_pk_fma_f32 v[34:35], v[162:163], v[104:105], v[34:35] op_sel_hi:[1,1,0] neg_lo:[0,0,1] neg_hi:[0,0,1]
	s_nop 0
	v_pk_fma_f32 v[104:105], v[34:35], v[34:35], v[102:103]
	v_mov_b32_e32 v102, v36
	v_mov_b32_e32 v103, v106
	v_mul_f32_e32 v36, v163, v106
	v_pk_fma_f32 v[102:103], v[162:163], v[102:103], v[36:37] op_sel_hi:[1,1,0] neg_lo:[0,0,1] neg_hi:[0,0,1]
	v_mov_b32_e32 v106, v37
	v_mul_f32_e32 v36, v163, v107
	v_pk_fma_f32 v[104:105], v[102:103], v[102:103], v[104:105]
	v_pk_fma_f32 v[36:37], v[162:163], v[106:107], v[36:37] op_sel_hi:[1,1,0] neg_lo:[0,0,1] neg_hi:[0,0,1]
	s_nop 0
	v_pk_fma_f32 v[106:107], v[36:37], v[36:37], v[104:105]
	v_mov_b32_e32 v104, v38
	v_mov_b32_e32 v105, v108
	v_mul_f32_e32 v38, v163, v108
	v_pk_fma_f32 v[104:105], v[162:163], v[104:105], v[38:39] op_sel_hi:[1,1,0] neg_lo:[0,0,1] neg_hi:[0,0,1]
; __device__ __forceinline__ void attnB_unit(const bf16* Q, const bf16* __restrict__ K, const bf16* __restrict__ V, bf16* O, long rowbase, int seq, int h, int q0, float lam, char* lds, LAS unsigned char* lds3) {
;     ...
;         for (int d0 = 0; d0 < 4; ++d0)
; #pragma unroll
;             for (int r = 0; r < 16; ++r) { const float v = o[d0][r] * rl - lam * X[(d0 * 16 + r) * 64]; o[d0][r] = v; ss += v * v; }
	v_mov_b32_e32 v108, v39
	v_mul_f32_e32 v38, v163, v109
	v_pk_fma_f32 v[106:107], v[104:105], v[104:105], v[106:107]
	v_pk_fma_f32 v[38:39], v[162:163], v[108:109], v[38:39] op_sel_hi:[1,1,0] neg_lo:[0,0,1] neg_hi:[0,0,1]
	s_nop 0
	v_pk_fma_f32 v[108:109], v[38:39], v[38:39], v[106:107]
	v_mov_b32_e32 v106, v40
	v_mov_b32_e32 v107, v110
	v_mul_f32_e32 v40, v163, v110
	v_pk_fma_f32 v[106:107], v[162:163], v[106:107], v[40:41] op_sel_hi:[1,1,0] neg_lo:[0,0,1] neg_hi:[0,0,1]
	v_mov_b32_e32 v110, v41
	v_mul_f32_e32 v40, v163, v111
	v_pk_fma_f32 v[108:109], v[106:107], v[106:107], v[108:109]
	v_pk_fma_f32 v[40:41], v[162:163], v[110:111], v[40:41] op_sel_hi:[1,1,0] neg_lo:[0,0,1] neg_hi:[0,0,1]
	s_nop 0
	v_pk_fma_f32 v[110:111], v[40:41], v[40:41], v[108:109]
	v_mov_b32_e32 v108, v42
	v_mov_b32_e32 v109, v112
	v_mul_f32_e32 v42, v163, v112
	v_pk_fma_f32 v[108:109], v[162:163], v[108:109], v[42:43] op_sel_hi:[1,1,0] neg_lo:[0,0,1] neg_hi:[0,0,1]
	v_mov_b32_e32 v112, v43
	v_mul_f32_e32 v42, v163, v113
	v_pk_fma_f32 v[110:111], v[108:109], v[108:109], v[110:111]
	v_pk_fma_f32 v[42:43], v[162:163], v[112:113], v[42:43] op_sel_hi:[1,1,0] neg_lo:[0,0,1] neg_hi:[0,0,1]
	s_nop 0
	v_pk_fma_f32 v[112:113], v[42:43], v[42:43], v[110:111]
	v_mov_b32_e32 v110, v44
	v_mov_b32_e32 v111, v114
	v_mul_f32_e32 v44, v163, v114
	v_pk_fma_f32 v[110:111], v[162:163], v[110:111], v[44:45] op_sel_hi:[1,1,0] neg_lo:[0,0,1] neg_hi:[0,0,1]
	v_mov_b32_e32 v114, v45
	v_mul_f32_e32 v44, v163, v115
	v_pk_fma_f32 v[112:113], v[110:111], v[110:111], v[112:113]
	v_pk_fma_f32 v[44:45], v[162:163], v[114:115], v[44:45] op_sel_hi:[1,1,0] neg_lo:[0,0,1] neg_hi:[0,0,1]
	s_nop 0
	v_pk_fma_f32 v[114:115], v[44:45], v[44:45], v[112:113]
	v_mov_b32_e32 v112, v46
	v_mov_b32_e32 v113, v116
	v_mul_f32_e32 v46, v163, v116
	v_pk_fma_f32 v[112:113], v[162:163], v[112:113], v[46:47] op_sel_hi:[1,1,0] neg_lo:[0,0,1] neg_hi:[0,0,1]
	v_mov_b32_e32 v116, v47
	v_mul_f32_e32 v46, v163, v117
	v_pk_fma_f32 v[114:115], v[112:113], v[112:113], v[114:115]
	v_pk_fma_f32 v[46:47], v[162:163], v[116:117], v[46:47] op_sel_hi:[1,1,0] neg_lo:[0,0,1] neg_hi:[0,0,1]
	s_nop 0
	v_pk_fma_f32 v[116:117], v[46:47], v[46:47], v[114:115]
	v_mov_b32_e32 v114, v48
	v_mov_b32_e32 v115, v118
	v_mul_f32_e32 v48, v163, v118
	v_pk_fma_f32 v[114:115], v[162:163], v[114:115], v[48:49] op_sel_hi:[1,1,0] neg_lo:[0,0,1] neg_hi:[0,0,1]
	v_mov_b32_e32 v118, v49
	v_mul_f32_e32 v48, v163, v119
	v_pk_fma_f32 v[116:117], v[114:115], v[114:115], v[116:117]
	v_pk_fma_f32 v[48:49], v[162:163], v[118:119], v[48:49] op_sel_hi:[1,1,0] neg_lo:[0,0,1] neg_hi:[0,0,1]
	s_nop 0
	v_pk_fma_f32 v[118:119], v[48:49], v[48:49], v[116:117]
	v_mov_b32_e32 v116, v18
	v_mov_b32_e32 v117, v120
	v_mul_f32_e32 v18, v163, v120
	v_pk_fma_f32 v[116:117], v[162:163], v[116:117], v[18:19] op_sel_hi:[1,1,0] neg_lo:[0,0,1] neg_hi:[0,0,1]
	v_mov_b32_e32 v120, v19
	v_mul_f32_e32 v18, v163, v121
	v_pk_fma_f32 v[118:119], v[116:117], v[116:117], v[118:119]
	v_pk_fma_f32 v[18:19], v[162:163], v[120:121], v[18:19] op_sel_hi:[1,1,0] neg_lo:[0,0,1] neg_hi:[0,0,1]
	s_nop 0
	v_pk_fma_f32 v[120:121], v[18:19], v[18:19], v[118:119]
	v_mov_b32_e32 v118, v20
	v_mov_b32_e32 v119, v122
	v_mul_f32_e32 v20, v163, v122
	v_pk_fma_f32 v[118:119], v[162:163], v[118:119], v[20:21] op_sel_hi:[1,1,0] neg_lo:[0,0,1] neg_hi:[0,0,1]
	v_mov_b32_e32 v122, v21
	v_mul_f32_e32 v20, v163, v123
	v_pk_fma_f32 v[120:121], v[118:119], v[118:119], v[120:121]
	v_pk_fma_f32 v[20:21], v[162:163], v[122:123], v[20:21] op_sel_hi:[1,1,0] neg_lo:[0,0,1] neg_hi:[0,0,1]
	s_nop 0
	v_pk_fma_f32 v[122:123], v[20:21], v[20:21], v[120:121]
	v_mov_b32_e32 v120, v22
	v_mov_b32_e32 v121, v124
	v_mul_f32_e32 v22, v163, v124
	v_pk_fma_f32 v[120:121], v[162:163], v[120:121], v[22:23] op_sel_hi:[1,1,0] neg_lo:[0,0,1] neg_hi:[0,0,1]
	v_mov_b32_e32 v124, v23
	v_mul_f32_e32 v22, v163, v125
	v_pk_fma_f32 v[122:123], v[120:121], v[120:121], v[122:123]
	v_pk_fma_f32 v[22:23], v[162:163], v[124:125], v[22:23] op_sel_hi:[1,1,0] neg_lo:[0,0,1] neg_hi:[0,0,1]
	s_nop 0
	v_pk_fma_f32 v[124:125], v[22:23], v[22:23], v[122:123]
	v_mov_b32_e32 v122, v24
	v_mov_b32_e32 v123, v126
	v_mul_f32_e32 v24, v163, v126
	v_pk_fma_f32 v[122:123], v[162:163], v[122:123], v[24:25] op_sel_hi:[1,1,0] neg_lo:[0,0,1] neg_hi:[0,0,1]
	v_mov_b32_e32 v126, v25
	v_mul_f32_e32 v24, v163, v127
	v_pk_fma_f32 v[124:125], v[122:123], v[122:123], v[124:125]
	v_pk_fma_f32 v[24:25], v[162:163], v[126:127], v[24:25] op_sel_hi:[1,1,0] neg_lo:[0,0,1] neg_hi:[0,0,1]
	s_nop 0
	v_pk_fma_f32 v[126:127], v[24:25], v[24:25], v[124:125]
	v_mov_b32_e32 v124, v26
	s_waitcnt lgkmcnt(2)
	v_mov_b32_e32 v125, v128
	v_mul_f32_e32 v26, v163, v128
	v_pk_fma_f32 v[124:125], v[162:163], v[124:125], v[26:27] op_sel_hi:[1,1,0] neg_lo:[0,0,1] neg_hi:[0,0,1]
	v_mov_b32_e32 v128, v27
	v_mul_f32_e32 v26, v163, v129
	v_pk_fma_f32 v[126:127], v[124:125], v[124:125], v[126:127]
	v_pk_fma_f32 v[26:27], v[162:163], v[128:129], v[26:27] op_sel_hi:[1,1,0] neg_lo:[0,0,1] neg_hi:[0,0,1]
	s_nop 0
	v_pk_fma_f32 v[128:129], v[26:27], v[26:27], v[126:127]
	v_mov_b32_e32 v126, v28
	s_waitcnt lgkmcnt(1)
	v_mov_b32_e32 v127, v130
	v_mul_f32_e32 v28, v163, v130
	v_pk_fma_f32 v[126:127], v[162:163], v[126:127], v[28:29] op_sel_hi:[1,1,0] neg_lo:[0,0,1] neg_hi:[0,0,1]
	v_mov_b32_e32 v130, v29
	v_mul_f32_e32 v28, v163, v131
	v_pk_fma_f32 v[128:129], v[126:127], v[126:127], v[128:129]
	v_pk_fma_f32 v[28:29], v[162:163], v[130:131], v[28:29] op_sel_hi:[1,1,0] neg_lo:[0,0,1] neg_hi:[0,0,1]
	s_nop 0
	v_pk_fma_f32 v[130:131], v[28:29], v[28:29], v[128:129]
	v_mov_b32_e32 v128, v30
	s_waitcnt lgkmcnt(0)
; __device__ __forceinline__ unsigned cvtpk(float lo, float hi) { unsigned r; asm volatile("v_cvt_pk_bf16_f32 %0, %1, %2" : "=v"(r) : "v"(lo), "v"(hi)); return r; }
; __device__ __forceinline__ void attnB_unit(const bf16* Q, const bf16* __restrict__ K, const bf16* __restrict__ V, bf16* O, long rowbase, int seq, int h, int q0, float lam, char* lds, LAS unsigned char* lds3) {
;     ...
;         { auto rr = __builtin_amdgcn_permlane32_swap(__float_as_uint(ss), __float_as_uint(ss), false, false); ss = __uint_as_float(rr[0]) + __uint_as_float(rr[1]); }
;         const float rs = __builtin_amdgcn_rsqf(ss * (1.f / 128.f) + RMS_EPS);
;         bf16* Ow = O + (size_t)(rowbase + q0 + wq * 32 + r32) * DM + h * 128 + 4 * hi;
; #pragma unroll
;         for (int d0 = 0; d0 < 4; ++d0)
; #pragma unroll
;             for (int g4 = 0; g4 < 4; ++g4) { u32x2 w; w.x = cvtpk(o[d0][4 * g4] * rs, o[d0][4 * g4 + 1] * rs); w.y = cvtpk(o[d0][4 * g4 + 2] * rs, o[d0][4 * g4 + 3] * rs);
;                 *(u32x2*)(Ow + d0 * 32 + 8 * g4) = w; }
	v_mov_b32_e32 v129, v132
	v_mul_f32_e32 v30, v163, v132
	v_pk_fma_f32 v[128:129], v[162:163], v[128:129], v[30:31] op_sel_hi:[1,1,0] neg_lo:[0,0,1] neg_hi:[0,0,1]
	v_mov_b32_e32 v132, v31
	v_mul_f32_e32 v30, v163, v133
	v_pk_fma_f32 v[30:31], v[162:163], v[132:133], v[30:31] op_sel_hi:[1,1,0] neg_lo:[0,0,1] neg_hi:[0,0,1]
	ds_read2st64_b32 v[132:133], v1 offset0:62 offset1:63
	v_pk_fma_f32 v[130:131], v[128:129], v[128:129], v[130:131]
	s_waitcnt lgkmcnt(0)
	v_pk_mul_f32 v[132:133], v[164:165], v[132:133]
	v_pk_fma_f32 v[130:131], v[30:31], v[30:31], v[130:131]
	v_pk_fma_f32 v[32:33], v[162:163], v[32:33], v[132:133] op_sel_hi:[0,1,1] neg_lo:[0,0,1] neg_hi:[0,0,1]
	v_pk_fma_f32 v[130:131], v[32:33], v[32:33], v[130:131]
	v_mul_f32_e32 v132, v33, v33
	v_pk_add_f32 v[130:131], v[130:131], v[132:133] op_sel_hi:[1,0]
	s_nop 0
	v_mov_b32_e32 v1, v130
	s_nop 1
	v_permlane32_swap_b32_e32 v130, v1
	v_add_f32_e32 v1, v130, v1
	v_fmamk_f32 v1, v1, 0x3c000000, v201
	v_rsq_f32_e32 v1, v1
	v_lshlrev_b32_e32 v130, 4, v17
	v_mov_b32_e32 v131, v0
	v_lshl_add_u64 v[130:131], v[166:167], 0, v[130:131]
	v_mul_f32_e32 v236, v2, v1
	v_mul_f32_e32 v246, v4, v1
	v_cvt_pk_bf16_f32 v236, v236, v246
	v_mul_f32_e32 v237, v6, v1
	v_mul_f32_e32 v246, v8, v1
	v_cvt_pk_bf16_f32 v237, v237, v246
	v_mul_f32_e32 v238, v10, v1
	v_mul_f32_e32 v246, v12, v1
	v_cvt_pk_bf16_f32 v238, v238, v246
	v_mul_f32_e32 v239, v14, v1
	v_mul_f32_e32 v246, v66, v1
	v_cvt_pk_bf16_f32 v239, v239, v246
	s_nop 1
	v_permlane32_swap_b32_e32 v236, v238
	v_permlane32_swap_b32_e32 v237, v239
	global_store_dwordx4 v[130:131], v[236:239], off
	v_mul_f32_e32 v240, v68, v1
	v_mul_f32_e32 v246, v70, v1
	v_cvt_pk_bf16_f32 v240, v240, v246
	v_mul_f32_e32 v241, v72, v1
	v_mul_f32_e32 v246, v74, v1
	v_cvt_pk_bf16_f32 v241, v241, v246
	v_mul_f32_e32 v242, v76, v1
	v_mul_f32_e32 v246, v78, v1
	v_cvt_pk_bf16_f32 v242, v242, v246
	v_mul_f32_e32 v243, v82, v1
	v_mul_f32_e32 v246, v80, v1
	v_cvt_pk_bf16_f32 v243, v243, v246
	s_nop 1
	v_permlane32_swap_b32_e32 v240, v242
	v_permlane32_swap_b32_e32 v241, v243
	global_store_dwordx4 v[130:131], v[240:243], off offset:32
	v_mul_f32_e32 v236, v84, v1
	v_mul_f32_e32 v246, v50, v1
	v_cvt_pk_bf16_f32 v236, v236, v246
	v_mul_f32_e32 v237, v86, v1
	v_mul_f32_e32 v246, v52, v1
	v_cvt_pk_bf16_f32 v237, v237, v246
	v_mul_f32_e32 v238, v88, v1
	v_mul_f32_e32 v246, v54, v1
	v_cvt_pk_bf16_f32 v238, v238, v246
	v_mul_f32_e32 v239, v90, v1
	v_mul_f32_e32 v246, v56, v1
	v_cvt_pk_bf16_f32 v239, v239, v246
	s_nop 1
	v_permlane32_swap_b32_e32 v236, v238
	v_permlane32_swap_b32_e32 v237, v239
	global_store_dwordx4 v[130:131], v[236:239], off offset:64
	v_mul_f32_e32 v240, v92, v1
	v_mul_f32_e32 v246, v58, v1
	v_cvt_pk_bf16_f32 v240, v240, v246
	v_mul_f32_e32 v241, v94, v1
	v_mul_f32_e32 v246, v60, v1
	v_cvt_pk_bf16_f32 v241, v241, v246
	v_mul_f32_e32 v242, v96, v1
	v_mul_f32_e32 v246, v62, v1
	v_cvt_pk_bf16_f32 v242, v242, v246
	v_mul_f32_e32 v243, v98, v1
	v_mul_f32_e32 v246, v64, v1
	v_cvt_pk_bf16_f32 v243, v243, v246
	s_nop 1
	v_permlane32_swap_b32_e32 v240, v242
	v_permlane32_swap_b32_e32 v241, v243
	global_store_dwordx4 v[130:131], v[240:243], off offset:96
	v_mul_f32_e32 v236, v100, v1
	v_mul_f32_e32 v246, v34, v1
	v_cvt_pk_bf16_f32 v236, v236, v246
	v_mul_f32_e32 v237, v102, v1
	v_mul_f32_e32 v246, v36, v1
	v_cvt_pk_bf16_f32 v237, v237, v246
	v_mul_f32_e32 v238, v104, v1
	v_mul_f32_e32 v246, v38, v1
	v_cvt_pk_bf16_f32 v238, v238, v246
	v_mul_f32_e32 v239, v106, v1
	v_mul_f32_e32 v246, v40, v1
	v_cvt_pk_bf16_f32 v239, v239, v246
	s_nop 1
	v_permlane32_swap_b32_e32 v236, v238
	v_permlane32_swap_b32_e32 v237, v239
	global_store_dwordx4 v[130:131], v[236:239], off offset:128
	v_mul_f32_e32 v240, v108, v1
	v_mul_f32_e32 v246, v42, v1
	v_cvt_pk_bf16_f32 v240, v240, v246
	v_mul_f32_e32 v241, v110, v1
	v_mul_f32_e32 v246, v44, v1
	v_cvt_pk_bf16_f32 v241, v241, v246
	v_mul_f32_e32 v242, v112, v1
	v_mul_f32_e32 v246, v46, v1
	v_cvt_pk_bf16_f32 v242, v242, v246
	v_mul_f32_e32 v243, v114, v1
	v_mul_f32_e32 v246, v48, v1
	v_cvt_pk_bf16_f32 v243, v243, v246
	s_nop 1
	v_permlane32_swap_b32_e32 v240, v242
	v_permlane32_swap_b32_e32 v241, v243
	global_store_dwordx4 v[130:131], v[240:243], off offset:160
	v_mul_f32_e32 v236, v116, v1
	v_mul_f32_e32 v246, v18, v1
	v_cvt_pk_bf16_f32 v236, v236, v246
	v_mul_f32_e32 v237, v118, v1
	v_mul_f32_e32 v246, v20, v1
	v_cvt_pk_bf16_f32 v237, v237, v246
	v_mul_f32_e32 v238, v120, v1
	v_mul_f32_e32 v246, v22, v1
	v_cvt_pk_bf16_f32 v238, v238, v246
	v_mul_f32_e32 v239, v122, v1
	v_mul_f32_e32 v246, v24, v1
	v_cvt_pk_bf16_f32 v239, v239, v246
	s_nop 1
	v_permlane32_swap_b32_e32 v236, v238
	v_permlane32_swap_b32_e32 v237, v239
	global_store_dwordx4 v[130:131], v[236:239], off offset:192
	v_mul_f32_e32 v240, v124, v1
	v_mul_f32_e32 v246, v26, v1
	v_cvt_pk_bf16_f32 v240, v240, v246
	v_mul_f32_e32 v241, v126, v1
	v_mul_f32_e32 v246, v28, v1
	v_cvt_pk_bf16_f32 v241, v241, v246
	v_mul_f32_e32 v242, v128, v1
	v_mul_f32_e32 v246, v30, v1
	v_cvt_pk_bf16_f32 v242, v242, v246
	v_mul_f32_e32 v243, v32, v1
	v_mul_f32_e32 v246, v33, v1
	v_cvt_pk_bf16_f32 v243, v243, v246
	s_nop 1
	v_permlane32_swap_b32_e32 v240, v242
	v_permlane32_swap_b32_e32 v241, v243
	global_store_dwordx4 v[130:131], v[240:243], off offset:224
	s_branch .LBB0_265
